# first K64 step of each FFN-up unit peeled with C=0 MFMAs instead of zeroing 128 accumulator registers
# speedup vs baseline: 1.0044x; 1.0008x over previous
.Lst1_skip:
	s_add_u32 s52, s30, 0x40080
	s_addc_u32 s53, s31, 0
	s_add_u32 s71, s28, 0x100
	s_addc_u32 s72, s29, 0
	s_mov_b32 s73, -2
	s_waitcnt lgkmcnt(0)
	ds_read_b128 v[148:151], v165
	ds_read_b128 v[152:155], v165 offset:1024
	ds_read_b128 v[156:159], v165 offset:2048
	ds_read_b128 v[160:163], v165 offset:3072
	ds_read_b128 v[170:173], v166
	ds_read_b128 v[174:177], v166 offset:1024
	ds_read_b128 v[178:181], v166 offset:2048
	ds_read_b128 v[182:185], v166 offset:3072
	s_add_u32 s28, s52, 0xfffc0080
	s_addc_u32 s29, s53, -1
	s_cmp_eq_u32 s73, 12
	s_cselect_b32 s31, s15, s29
	s_cselect_b32 s30, s69, s28
	s_cselect_b32 s29, s13, s72
	s_cselect_b32 s28, s70, s71
	s_add_i32 m0, s21, 0xc000
	ds_read_b128 v[186:189], v167
	ds_read_b128 v[190:193], v167 offset:1024
	ds_read_b128 v[194:197], v167 offset:2048
	ds_read_b128 v[198:201], v167 offset:3072
	ds_read_b128 v[202:205], v167 offset:4096
	ds_read_b128 v[206:209], v167 offset:5120
	ds_read_b128 v[210:213], v167 offset:6144
	ds_read_b128 v[214:217], v167 offset:7168
	global_load_lds_dwordx4 v140, s[52:53]
	s_add_i32 m0, s21, 0xe000
	s_nop 0
	global_load_lds_dwordx4 v142, s[52:53]
	s_waitcnt vmcnt(8)
	s_waitcnt lgkmcnt(0)
	s_barrier
	v_mfma_f32_16x16x32_bf16 v[126:129], v[148:151], v[186:189], 0
	v_mfma_f32_16x16x32_bf16 v[118:121], v[156:159], v[186:189], 0
	v_mfma_f32_16x16x32_bf16 v[110:113], v[148:151], v[194:197], 0
	v_mfma_f32_16x16x32_bf16 v[102:105], v[156:159], v[194:197], 0
	v_mfma_f32_16x16x32_bf16 v[94:97], v[148:151], v[202:205], 0
	v_mfma_f32_16x16x32_bf16 v[86:89], v[156:159], v[202:205], 0
	v_mfma_f32_16x16x32_bf16 v[78:81], v[148:151], v[210:213], 0
	v_mfma_f32_16x16x32_bf16 v[70:73], v[156:159], v[210:213], 0
	v_mfma_f32_16x16x32_bf16 v[126:129], v[152:155], v[190:193], v[126:129]
	v_mfma_f32_16x16x32_bf16 v[118:121], v[160:163], v[190:193], v[118:121]
	v_mfma_f32_16x16x32_bf16 v[110:113], v[152:155], v[198:201], v[110:113]
	v_mfma_f32_16x16x32_bf16 v[102:105], v[160:163], v[198:201], v[102:105]
	v_mfma_f32_16x16x32_bf16 v[94:97], v[152:155], v[206:209], v[94:97]
	v_mfma_f32_16x16x32_bf16 v[86:89], v[160:163], v[206:209], v[86:89]
	v_mfma_f32_16x16x32_bf16 v[78:81], v[152:155], v[214:217], v[78:81]
	v_mfma_f32_16x16x32_bf16 v[70:73], v[160:163], v[214:217], v[70:73]
	v_mfma_f32_16x16x32_bf16 v[122:125], v[170:173], v[186:189], 0
	v_mfma_f32_16x16x32_bf16 v[114:117], v[178:181], v[186:189], 0
	v_mfma_f32_16x16x32_bf16 v[106:109], v[170:173], v[194:197], 0
	v_mfma_f32_16x16x32_bf16 v[98:101], v[178:181], v[194:197], 0
	v_mfma_f32_16x16x32_bf16 v[90:93], v[170:173], v[202:205], 0
	v_mfma_f32_16x16x32_bf16 v[82:85], v[178:181], v[202:205], 0
	v_mfma_f32_16x16x32_bf16 v[74:77], v[170:173], v[210:213], 0
	v_mfma_f32_16x16x32_bf16 v[66:69], v[178:181], v[210:213], 0
	v_mfma_f32_16x16x32_bf16 v[122:125], v[174:177], v[190:193], v[122:125]
	v_mfma_f32_16x16x32_bf16 v[114:117], v[182:185], v[190:193], v[114:117]
	v_mfma_f32_16x16x32_bf16 v[106:109], v[174:177], v[198:201], v[106:109]
	v_mfma_f32_16x16x32_bf16 v[98:101], v[182:185], v[198:201], v[98:101]
	v_mfma_f32_16x16x32_bf16 v[90:93], v[174:177], v[206:209], v[90:93]
	v_mfma_f32_16x16x32_bf16 v[82:85], v[182:185], v[206:209], v[82:85]
	v_mfma_f32_16x16x32_bf16 v[74:77], v[174:177], v[214:217], v[74:77]
	v_mfma_f32_16x16x32_bf16 v[66:69], v[182:185], v[214:217], v[66:69]
	s_barrier
	s_add_i32 s74, s59, s24
	s_mov_b32 m0, s74
	ds_read_b128 v[186:189], v167 offset:16384
	ds_read_b128 v[190:193], v167 offset:17408
	ds_read_b128 v[194:197], v167 offset:18432
	ds_read_b128 v[198:201], v167 offset:19456
	ds_read_b128 v[202:205], v167 offset:20480
	ds_read_b128 v[206:209], v167 offset:21504
	ds_read_b128 v[210:213], v167 offset:22528
	ds_read_b128 v[214:217], v167 offset:23552
	global_load_lds_dwordx4 v134, s[28:29]
	s_add_i32 m0, s74, 0x2000
	s_add_u32 s74, s28, 0x40000
	s_addc_u32 s75, s29, 0
	s_add_i32 s76, s66, s24
	global_load_lds_dwordx4 v130, s[28:29]
	s_mov_b32 m0, s76
	s_nop 0
	global_load_lds_dwordx4 v134, s[74:75]
	s_add_i32 m0, s76, 0x2000
	s_nop 0
	global_load_lds_dwordx4 v130, s[74:75]
	s_mov_b32 m0, s21
	s_nop 0
	global_load_lds_dwordx4 v136, s[30:31]
	s_mov_b32 m0, s34
	s_nop 0
	global_load_lds_dwordx4 v132, s[30:31]
	s_waitcnt vmcnt(8)
	s_waitcnt lgkmcnt(0)
	s_barrier
	v_mfma_f32_16x16x32_bf16 v[62:65], v[148:151], v[186:189], 0
	v_mfma_f32_16x16x32_bf16 v[54:57], v[156:159], v[186:189], 0
	v_mfma_f32_16x16x32_bf16 v[46:49], v[148:151], v[194:197], 0
	v_mfma_f32_16x16x32_bf16 v[38:41], v[156:159], v[194:197], 0
	v_mfma_f32_16x16x32_bf16 v[30:33], v[148:151], v[202:205], 0
	v_mfma_f32_16x16x32_bf16 v[22:25], v[156:159], v[202:205], 0
	v_mfma_f32_16x16x32_bf16 v[14:17], v[148:151], v[210:213], 0
	v_mfma_f32_16x16x32_bf16 v[6:9], v[156:159], v[210:213], 0
	v_mfma_f32_16x16x32_bf16 v[62:65], v[152:155], v[190:193], v[62:65]
	v_mfma_f32_16x16x32_bf16 v[54:57], v[160:163], v[190:193], v[54:57]
	v_mfma_f32_16x16x32_bf16 v[46:49], v[152:155], v[198:201], v[46:49]
	v_mfma_f32_16x16x32_bf16 v[38:41], v[160:163], v[198:201], v[38:41]
	v_mfma_f32_16x16x32_bf16 v[30:33], v[152:155], v[206:209], v[30:33]
	v_mfma_f32_16x16x32_bf16 v[22:25], v[160:163], v[206:209], v[22:25]
	v_mfma_f32_16x16x32_bf16 v[14:17], v[152:155], v[214:217], v[14:17]
	v_mfma_f32_16x16x32_bf16 v[6:9], v[160:163], v[214:217], v[6:9]
	v_mfma_f32_16x16x32_bf16 v[58:61], v[170:173], v[186:189], 0
	v_mfma_f32_16x16x32_bf16 v[50:53], v[178:181], v[186:189], 0
	v_mfma_f32_16x16x32_bf16 v[42:45], v[170:173], v[194:197], 0
	v_mfma_f32_16x16x32_bf16 v[34:37], v[178:181], v[194:197], 0
	v_mfma_f32_16x16x32_bf16 v[26:29], v[170:173], v[202:205], 0
	v_mfma_f32_16x16x32_bf16 v[18:21], v[178:181], v[202:205], 0
	v_mfma_f32_16x16x32_bf16 v[10:13], v[170:173], v[210:213], 0
	v_mfma_f32_16x16x32_bf16 v[2:5], v[178:181], v[210:213], 0
	v_mfma_f32_16x16x32_bf16 v[58:61], v[174:177], v[190:193], v[58:61]
	v_mfma_f32_16x16x32_bf16 v[50:53], v[182:185], v[190:193], v[50:53]
	v_mfma_f32_16x16x32_bf16 v[42:45], v[174:177], v[198:201], v[42:45]
	v_mfma_f32_16x16x32_bf16 v[34:37], v[182:185], v[198:201], v[34:37]
	v_mfma_f32_16x16x32_bf16 v[26:29], v[174:177], v[206:209], v[26:29]
	v_mfma_f32_16x16x32_bf16 v[18:21], v[182:185], v[206:209], v[18:21]
	v_mfma_f32_16x16x32_bf16 v[10:13], v[174:177], v[214:217], v[10:13]
	v_mfma_f32_16x16x32_bf16 v[2:5], v[182:185], v[214:217], v[2:5]
	s_barrier
	s_branch .Lpeel170_seg3

.Lpeel170_seg3:
	s_add_i32 s74, 0, 0x18000
	s_add_i32 s75, 0, 0x1c000
	ds_read_b128 v[148:151], v165 offset:32768
	ds_read_b128 v[152:155], v165 offset:33792
	ds_read_b128 v[156:159], v165 offset:34816
	ds_read_b128 v[160:163], v165 offset:35840
	ds_read_b128 v[170:173], v166 offset:32768
	ds_read_b128 v[174:177], v166 offset:33792
	ds_read_b128 v[178:181], v166 offset:34816
	ds_read_b128 v[182:185], v166 offset:35840
	s_add_u32 s98, s30, 0x40000
	s_addc_u32 s99, s31, 0
	s_mov_b32 m0, s35
	ds_read_b128 v[186:189], v167 offset:32768
	ds_read_b128 v[190:193], v167 offset:33792
	ds_read_b128 v[194:197], v167 offset:34816
	ds_read_b128 v[198:201], v167 offset:35840
	ds_read_b128 v[202:205], v167 offset:36864
	ds_read_b128 v[206:209], v167 offset:37888
	ds_read_b128 v[210:213], v167 offset:38912
	ds_read_b128 v[214:217], v167 offset:39936
	global_load_lds_dwordx4 v136, s[98:99]
	s_mov_b32 m0, s54
	s_nop 0
	global_load_lds_dwordx4 v132, s[98:99]
	s_waitcnt vmcnt(8)
	s_waitcnt lgkmcnt(0)
	s_barrier
	v_mfma_f32_16x16x32_bf16 v[126:129], v[148:151], v[186:189], v[126:129]
	v_mfma_f32_16x16x32_bf16 v[118:121], v[156:159], v[186:189], v[118:121]
	v_mfma_f32_16x16x32_bf16 v[110:113], v[148:151], v[194:197], v[110:113]
	v_mfma_f32_16x16x32_bf16 v[102:105], v[156:159], v[194:197], v[102:105]
	v_mfma_f32_16x16x32_bf16 v[94:97], v[148:151], v[202:205], v[94:97]
	v_mfma_f32_16x16x32_bf16 v[86:89], v[156:159], v[202:205], v[86:89]
	v_mfma_f32_16x16x32_bf16 v[78:81], v[148:151], v[210:213], v[78:81]
	v_mfma_f32_16x16x32_bf16 v[70:73], v[156:159], v[210:213], v[70:73]
	v_mfma_f32_16x16x32_bf16 v[126:129], v[152:155], v[190:193], v[126:129]
	v_mfma_f32_16x16x32_bf16 v[118:121], v[160:163], v[190:193], v[118:121]
	v_mfma_f32_16x16x32_bf16 v[110:113], v[152:155], v[198:201], v[110:113]
	v_mfma_f32_16x16x32_bf16 v[102:105], v[160:163], v[198:201], v[102:105]
	v_mfma_f32_16x16x32_bf16 v[94:97], v[152:155], v[206:209], v[94:97]
	v_mfma_f32_16x16x32_bf16 v[86:89], v[160:163], v[206:209], v[86:89]
	v_mfma_f32_16x16x32_bf16 v[78:81], v[152:155], v[214:217], v[78:81]
	v_mfma_f32_16x16x32_bf16 v[70:73], v[160:163], v[214:217], v[70:73]
	v_mfma_f32_16x16x32_bf16 v[122:125], v[170:173], v[186:189], v[122:125]
	v_mfma_f32_16x16x32_bf16 v[114:117], v[178:181], v[186:189], v[114:117]
	v_mfma_f32_16x16x32_bf16 v[106:109], v[170:173], v[194:197], v[106:109]
	v_mfma_f32_16x16x32_bf16 v[98:101], v[178:181], v[194:197], v[98:101]
	v_mfma_f32_16x16x32_bf16 v[90:93], v[170:173], v[202:205], v[90:93]
	v_mfma_f32_16x16x32_bf16 v[82:85], v[178:181], v[202:205], v[82:85]
	v_mfma_f32_16x16x32_bf16 v[74:77], v[170:173], v[210:213], v[74:77]
	v_mfma_f32_16x16x32_bf16 v[66:69], v[178:181], v[210:213], v[66:69]
	v_mfma_f32_16x16x32_bf16 v[122:125], v[174:177], v[190:193], v[122:125]
	v_mfma_f32_16x16x32_bf16 v[114:117], v[182:185], v[190:193], v[114:117]
	v_mfma_f32_16x16x32_bf16 v[106:109], v[174:177], v[198:201], v[106:109]
	v_mfma_f32_16x16x32_bf16 v[98:101], v[182:185], v[198:201], v[98:101]
	v_mfma_f32_16x16x32_bf16 v[90:93], v[174:177], v[206:209], v[90:93]
	v_mfma_f32_16x16x32_bf16 v[82:85], v[182:185], v[206:209], v[82:85]
	v_mfma_f32_16x16x32_bf16 v[74:77], v[174:177], v[214:217], v[74:77]
	v_mfma_f32_16x16x32_bf16 v[66:69], v[182:185], v[214:217], v[66:69]
	s_barrier
	s_add_i32 s98, s74, s24
	s_add_i32 m0, s98, 0xffffff80
	ds_read_b128 v[186:189], v167 offset:49152
	ds_read_b128 v[190:193], v167 offset:50176
	ds_read_b128 v[194:197], v167 offset:51200
	ds_read_b128 v[198:201], v167 offset:52224
	ds_read_b128 v[202:205], v167 offset:53248
	ds_read_b128 v[206:209], v167 offset:54272
	ds_read_b128 v[210:213], v167 offset:55296
	ds_read_b128 v[214:217], v167 offset:56320
	global_load_lds_dwordx4 v134, s[28:29] offset:128
	s_add_i32 m0, s98, 0x1f80
	s_add_i32 s98, s75, s24
	global_load_lds_dwordx4 v130, s[28:29] offset:128
	s_add_u32 s28, s28, 0x40080
	s_addc_u32 s29, s29, 0
	s_mov_b32 m0, s98
	s_nop 0
	global_load_lds_dwordx4 v134, s[28:29]
	s_add_i32 m0, s98, 0x2000
	s_nop 0
	global_load_lds_dwordx4 v130, s[28:29]
	s_add_i32 m0, s56, 0xffffff80
	s_nop 0
	global_load_lds_dwordx4 v136, s[30:31] offset:128
	s_add_i32 m0, s57, 0xffffff80
	s_nop 0
	global_load_lds_dwordx4 v132, s[30:31] offset:128
	s_waitcnt vmcnt(8)
	s_waitcnt lgkmcnt(0)
	s_barrier
	v_mfma_f32_16x16x32_bf16 v[62:65], v[148:151], v[186:189], v[62:65]
	v_mfma_f32_16x16x32_bf16 v[54:57], v[156:159], v[186:189], v[54:57]
	v_mfma_f32_16x16x32_bf16 v[46:49], v[148:151], v[194:197], v[46:49]
	v_mfma_f32_16x16x32_bf16 v[38:41], v[156:159], v[194:197], v[38:41]
	v_mfma_f32_16x16x32_bf16 v[30:33], v[148:151], v[202:205], v[30:33]
	v_mfma_f32_16x16x32_bf16 v[22:25], v[156:159], v[202:205], v[22:25]
	v_mfma_f32_16x16x32_bf16 v[14:17], v[148:151], v[210:213], v[14:17]
	v_mfma_f32_16x16x32_bf16 v[6:9], v[156:159], v[210:213], v[6:9]
	v_mfma_f32_16x16x32_bf16 v[62:65], v[152:155], v[190:193], v[62:65]
	v_mfma_f32_16x16x32_bf16 v[54:57], v[160:163], v[190:193], v[54:57]
	v_mfma_f32_16x16x32_bf16 v[46:49], v[152:155], v[198:201], v[46:49]
	v_mfma_f32_16x16x32_bf16 v[38:41], v[160:163], v[198:201], v[38:41]
	v_mfma_f32_16x16x32_bf16 v[30:33], v[152:155], v[206:209], v[30:33]
	v_mfma_f32_16x16x32_bf16 v[22:25], v[160:163], v[206:209], v[22:25]
	v_mfma_f32_16x16x32_bf16 v[14:17], v[152:155], v[214:217], v[14:17]
	v_mfma_f32_16x16x32_bf16 v[6:9], v[160:163], v[214:217], v[6:9]
	v_mfma_f32_16x16x32_bf16 v[58:61], v[170:173], v[186:189], v[58:61]
	v_mfma_f32_16x16x32_bf16 v[50:53], v[178:181], v[186:189], v[50:53]
	v_mfma_f32_16x16x32_bf16 v[42:45], v[170:173], v[194:197], v[42:45]
	v_mfma_f32_16x16x32_bf16 v[34:37], v[178:181], v[194:197], v[34:37]
	v_mfma_f32_16x16x32_bf16 v[26:29], v[170:173], v[202:205], v[26:29]
	v_mfma_f32_16x16x32_bf16 v[18:21], v[178:181], v[202:205], v[18:21]
	v_mfma_f32_16x16x32_bf16 v[10:13], v[170:173], v[210:213], v[10:13]
	v_mfma_f32_16x16x32_bf16 v[2:5], v[178:181], v[210:213], v[2:5]
	v_mfma_f32_16x16x32_bf16 v[58:61], v[174:177], v[190:193], v[58:61]
	v_mfma_f32_16x16x32_bf16 v[50:53], v[182:185], v[190:193], v[50:53]
	v_mfma_f32_16x16x32_bf16 v[42:45], v[174:177], v[198:201], v[42:45]
	v_mfma_f32_16x16x32_bf16 v[34:37], v[182:185], v[198:201], v[34:37]
	v_mfma_f32_16x16x32_bf16 v[26:29], v[174:177], v[206:209], v[26:29]
	v_mfma_f32_16x16x32_bf16 v[18:21], v[182:185], v[206:209], v[18:21]
	v_mfma_f32_16x16x32_bf16 v[10:13], v[174:177], v[214:217], v[10:13]
	v_mfma_f32_16x16x32_bf16 v[2:5], v[182:185], v[214:217], v[2:5]
	s_barrier
	s_add_i32 s73, s73, 2
	s_add_u32 s52, s52, 0x100
	s_addc_u32 s53, s53, 0
	s_add_u32 s71, s71, 0x100
	s_addc_u32 s72, s72, 0
	s_cmp_gt_u32 s73, 13
	s_cbranch_scc0 .LBB0_170
	s_and_b64 vcc, exec, s[10:11]
	s_cbranch_vccz .LBB0_173
	s_barrier

.Lst8_skip:
	s_add_u32 s58, s30, 0x40080
	s_addc_u32 s59, s31, 0
	s_add_u32 s72, s28, 0x100
	s_addc_u32 s73, s29, 0
	s_mov_b32 s74, -2
	s_waitcnt vmcnt(0)
	ds_read_b128 v[148:151], v165
	ds_read_b128 v[152:155], v165 offset:1024
	ds_read_b128 v[156:159], v165 offset:2048
	ds_read_b128 v[160:163], v165 offset:3072
	ds_read_b128 v[170:173], v166
	ds_read_b128 v[174:177], v166 offset:1024
	ds_read_b128 v[178:181], v166 offset:2048
	ds_read_b128 v[182:185], v166 offset:3072
	s_add_u32 s28, s58, 0xfffc0080
	s_addc_u32 s29, s59, -1
	s_cmp_eq_u32 s74, 12
	s_cselect_b32 s31, s51, s29
	s_cselect_b32 s30, s60, s28
	s_cselect_b32 s29, s49, s73
	s_cselect_b32 s28, s61, s72
	s_add_i32 m0, s33, 0xc000
	ds_read_b128 v[186:189], v167
	ds_read_b128 v[190:193], v167 offset:1024
	ds_read_b128 v[194:197], v167 offset:2048
	ds_read_b128 v[198:201], v167 offset:3072
	ds_read_b128 v[202:205], v167 offset:4096
	ds_read_b128 v[206:209], v167 offset:5120
	ds_read_b128 v[210:213], v167 offset:6144
	ds_read_b128 v[214:217], v167 offset:7168
	global_load_lds_dwordx4 v140, s[58:59]
	s_add_i32 m0, s33, 0xe000
	s_nop 0
	global_load_lds_dwordx4 v142, s[58:59]
	s_waitcnt vmcnt(8)
	s_waitcnt lgkmcnt(0)
	s_barrier
	v_mfma_f32_16x16x32_bf16 v[126:129], v[148:151], v[186:189], 0
	v_mfma_f32_16x16x32_bf16 v[118:121], v[156:159], v[186:189], 0
	v_mfma_f32_16x16x32_bf16 v[110:113], v[148:151], v[194:197], 0
	v_mfma_f32_16x16x32_bf16 v[102:105], v[156:159], v[194:197], 0
	v_mfma_f32_16x16x32_bf16 v[94:97], v[148:151], v[202:205], 0
	v_mfma_f32_16x16x32_bf16 v[86:89], v[156:159], v[202:205], 0
	v_mfma_f32_16x16x32_bf16 v[78:81], v[148:151], v[210:213], 0
	v_mfma_f32_16x16x32_bf16 v[70:73], v[156:159], v[210:213], 0
	v_mfma_f32_16x16x32_bf16 v[126:129], v[152:155], v[190:193], v[126:129]
	v_mfma_f32_16x16x32_bf16 v[118:121], v[160:163], v[190:193], v[118:121]
	v_mfma_f32_16x16x32_bf16 v[110:113], v[152:155], v[198:201], v[110:113]
	v_mfma_f32_16x16x32_bf16 v[102:105], v[160:163], v[198:201], v[102:105]
	v_mfma_f32_16x16x32_bf16 v[94:97], v[152:155], v[206:209], v[94:97]
	v_mfma_f32_16x16x32_bf16 v[86:89], v[160:163], v[206:209], v[86:89]
	v_mfma_f32_16x16x32_bf16 v[78:81], v[152:155], v[214:217], v[78:81]
	v_mfma_f32_16x16x32_bf16 v[70:73], v[160:163], v[214:217], v[70:73]
	v_mfma_f32_16x16x32_bf16 v[122:125], v[170:173], v[186:189], 0
	v_mfma_f32_16x16x32_bf16 v[114:117], v[178:181], v[186:189], 0
	v_mfma_f32_16x16x32_bf16 v[106:109], v[170:173], v[194:197], 0
	v_mfma_f32_16x16x32_bf16 v[98:101], v[178:181], v[194:197], 0
	v_mfma_f32_16x16x32_bf16 v[90:93], v[170:173], v[202:205], 0
	v_mfma_f32_16x16x32_bf16 v[82:85], v[178:181], v[202:205], 0
	v_mfma_f32_16x16x32_bf16 v[74:77], v[170:173], v[210:213], 0
	v_mfma_f32_16x16x32_bf16 v[66:69], v[178:181], v[210:213], 0
	v_mfma_f32_16x16x32_bf16 v[122:125], v[174:177], v[190:193], v[122:125]
	v_mfma_f32_16x16x32_bf16 v[114:117], v[182:185], v[190:193], v[114:117]
	v_mfma_f32_16x16x32_bf16 v[106:109], v[174:177], v[198:201], v[106:109]
	v_mfma_f32_16x16x32_bf16 v[98:101], v[182:185], v[198:201], v[98:101]
	v_mfma_f32_16x16x32_bf16 v[90:93], v[174:177], v[206:209], v[90:93]
	v_mfma_f32_16x16x32_bf16 v[82:85], v[182:185], v[206:209], v[82:85]
	v_mfma_f32_16x16x32_bf16 v[74:77], v[174:177], v[214:217], v[74:77]
	v_mfma_f32_16x16x32_bf16 v[66:69], v[182:185], v[214:217], v[66:69]
	s_barrier
	s_add_i32 s75, s67, s23
	s_mov_b32 m0, s75
	ds_read_b128 v[186:189], v167 offset:16384
	ds_read_b128 v[190:193], v167 offset:17408
	ds_read_b128 v[194:197], v167 offset:18432
	ds_read_b128 v[198:201], v167 offset:19456
	ds_read_b128 v[202:205], v167 offset:20480
	ds_read_b128 v[206:209], v167 offset:21504
	ds_read_b128 v[210:213], v167 offset:22528
	ds_read_b128 v[214:217], v167 offset:23552
	global_load_lds_dwordx4 v132, s[28:29]
	s_add_i32 m0, s75, 0x2000
	s_add_u32 s76, s28, 0x40000
	s_addc_u32 s77, s29, 0
	s_add_i32 s75, s68, s23
	global_load_lds_dwordx4 v136, s[28:29]
	s_mov_b32 m0, s75
	s_nop 0
	global_load_lds_dwordx4 v132, s[76:77]
	s_add_i32 m0, s75, 0x2000
	s_nop 0
	global_load_lds_dwordx4 v136, s[76:77]
	s_mov_b32 m0, s33
	s_nop 0
	global_load_lds_dwordx4 v130, s[30:31]
	s_mov_b32 m0, s34
	s_nop 0
	global_load_lds_dwordx4 v134, s[30:31]
	s_waitcnt vmcnt(8)
	s_waitcnt lgkmcnt(0)
	s_barrier
	v_mfma_f32_16x16x32_bf16 v[62:65], v[148:151], v[186:189], 0
	v_mfma_f32_16x16x32_bf16 v[54:57], v[156:159], v[186:189], 0
	v_mfma_f32_16x16x32_bf16 v[46:49], v[148:151], v[194:197], 0
	v_mfma_f32_16x16x32_bf16 v[38:41], v[156:159], v[194:197], 0
	v_mfma_f32_16x16x32_bf16 v[30:33], v[148:151], v[202:205], 0
	v_mfma_f32_16x16x32_bf16 v[22:25], v[156:159], v[202:205], 0
	v_mfma_f32_16x16x32_bf16 v[14:17], v[148:151], v[210:213], 0
	v_mfma_f32_16x16x32_bf16 v[6:9], v[156:159], v[210:213], 0
	v_mfma_f32_16x16x32_bf16 v[62:65], v[152:155], v[190:193], v[62:65]
	v_mfma_f32_16x16x32_bf16 v[54:57], v[160:163], v[190:193], v[54:57]
	v_mfma_f32_16x16x32_bf16 v[46:49], v[152:155], v[198:201], v[46:49]
	v_mfma_f32_16x16x32_bf16 v[38:41], v[160:163], v[198:201], v[38:41]
	v_mfma_f32_16x16x32_bf16 v[30:33], v[152:155], v[206:209], v[30:33]
	v_mfma_f32_16x16x32_bf16 v[22:25], v[160:163], v[206:209], v[22:25]
	v_mfma_f32_16x16x32_bf16 v[14:17], v[152:155], v[214:217], v[14:17]
	v_mfma_f32_16x16x32_bf16 v[6:9], v[160:163], v[214:217], v[6:9]
	v_mfma_f32_16x16x32_bf16 v[58:61], v[170:173], v[186:189], 0
	v_mfma_f32_16x16x32_bf16 v[50:53], v[178:181], v[186:189], 0
	v_mfma_f32_16x16x32_bf16 v[42:45], v[170:173], v[194:197], 0
	v_mfma_f32_16x16x32_bf16 v[34:37], v[178:181], v[194:197], 0
	v_mfma_f32_16x16x32_bf16 v[26:29], v[170:173], v[202:205], 0
	v_mfma_f32_16x16x32_bf16 v[18:21], v[178:181], v[202:205], 0
	v_mfma_f32_16x16x32_bf16 v[10:13], v[170:173], v[210:213], 0
	v_mfma_f32_16x16x32_bf16 v[2:5], v[178:181], v[210:213], 0
	v_mfma_f32_16x16x32_bf16 v[58:61], v[174:177], v[190:193], v[58:61]
	v_mfma_f32_16x16x32_bf16 v[50:53], v[182:185], v[190:193], v[50:53]
	v_mfma_f32_16x16x32_bf16 v[42:45], v[174:177], v[198:201], v[42:45]
	v_mfma_f32_16x16x32_bf16 v[34:37], v[182:185], v[198:201], v[34:37]
	v_mfma_f32_16x16x32_bf16 v[26:29], v[174:177], v[206:209], v[26:29]
	v_mfma_f32_16x16x32_bf16 v[18:21], v[182:185], v[206:209], v[18:21]
	v_mfma_f32_16x16x32_bf16 v[10:13], v[174:177], v[214:217], v[10:13]
	v_mfma_f32_16x16x32_bf16 v[2:5], v[182:185], v[214:217], v[2:5]
	s_barrier
	s_branch .Lpeel1905_seg3

.Lpeel1905_seg3:
	s_add_i32 s75, 0, 0x18000
	s_add_i32 s76, 0, 0x1c000
	ds_read_b128 v[148:151], v165 offset:32768
	ds_read_b128 v[152:155], v165 offset:33792
	ds_read_b128 v[156:159], v165 offset:34816
	ds_read_b128 v[160:163], v165 offset:35840
	ds_read_b128 v[170:173], v166 offset:32768
	ds_read_b128 v[174:177], v166 offset:33792
	ds_read_b128 v[178:181], v166 offset:34816
	ds_read_b128 v[182:185], v166 offset:35840
	s_add_u32 s98, s30, 0x40000
	s_addc_u32 s99, s31, 0
	s_mov_b32 m0, s35
	ds_read_b128 v[186:189], v167 offset:32768
	ds_read_b128 v[190:193], v167 offset:33792
	ds_read_b128 v[194:197], v167 offset:34816
	ds_read_b128 v[198:201], v167 offset:35840
	ds_read_b128 v[202:205], v167 offset:36864
	ds_read_b128 v[206:209], v167 offset:37888
	ds_read_b128 v[210:213], v167 offset:38912
	ds_read_b128 v[214:217], v167 offset:39936
	global_load_lds_dwordx4 v130, s[98:99]
	s_mov_b32 m0, s57
	s_nop 0
	global_load_lds_dwordx4 v134, s[98:99]
	s_waitcnt vmcnt(8)
	s_waitcnt lgkmcnt(0)
	s_barrier
	v_mfma_f32_16x16x32_bf16 v[126:129], v[148:151], v[186:189], v[126:129]
	v_mfma_f32_16x16x32_bf16 v[118:121], v[156:159], v[186:189], v[118:121]
	v_mfma_f32_16x16x32_bf16 v[110:113], v[148:151], v[194:197], v[110:113]
	v_mfma_f32_16x16x32_bf16 v[102:105], v[156:159], v[194:197], v[102:105]
	v_mfma_f32_16x16x32_bf16 v[94:97], v[148:151], v[202:205], v[94:97]
	v_mfma_f32_16x16x32_bf16 v[86:89], v[156:159], v[202:205], v[86:89]
	v_mfma_f32_16x16x32_bf16 v[78:81], v[148:151], v[210:213], v[78:81]
	v_mfma_f32_16x16x32_bf16 v[70:73], v[156:159], v[210:213], v[70:73]
	v_mfma_f32_16x16x32_bf16 v[126:129], v[152:155], v[190:193], v[126:129]
	v_mfma_f32_16x16x32_bf16 v[118:121], v[160:163], v[190:193], v[118:121]
	v_mfma_f32_16x16x32_bf16 v[110:113], v[152:155], v[198:201], v[110:113]
	v_mfma_f32_16x16x32_bf16 v[102:105], v[160:163], v[198:201], v[102:105]
	v_mfma_f32_16x16x32_bf16 v[94:97], v[152:155], v[206:209], v[94:97]
	v_mfma_f32_16x16x32_bf16 v[86:89], v[160:163], v[206:209], v[86:89]
	v_mfma_f32_16x16x32_bf16 v[78:81], v[152:155], v[214:217], v[78:81]
	v_mfma_f32_16x16x32_bf16 v[70:73], v[160:163], v[214:217], v[70:73]
	v_mfma_f32_16x16x32_bf16 v[122:125], v[170:173], v[186:189], v[122:125]
	v_mfma_f32_16x16x32_bf16 v[114:117], v[178:181], v[186:189], v[114:117]
	v_mfma_f32_16x16x32_bf16 v[106:109], v[170:173], v[194:197], v[106:109]
	v_mfma_f32_16x16x32_bf16 v[98:101], v[178:181], v[194:197], v[98:101]
	v_mfma_f32_16x16x32_bf16 v[90:93], v[170:173], v[202:205], v[90:93]
	v_mfma_f32_16x16x32_bf16 v[82:85], v[178:181], v[202:205], v[82:85]
	v_mfma_f32_16x16x32_bf16 v[74:77], v[170:173], v[210:213], v[74:77]
	v_mfma_f32_16x16x32_bf16 v[66:69], v[178:181], v[210:213], v[66:69]
	v_mfma_f32_16x16x32_bf16 v[122:125], v[174:177], v[190:193], v[122:125]
	v_mfma_f32_16x16x32_bf16 v[114:117], v[182:185], v[190:193], v[114:117]
	v_mfma_f32_16x16x32_bf16 v[106:109], v[174:177], v[198:201], v[106:109]
	v_mfma_f32_16x16x32_bf16 v[98:101], v[182:185], v[198:201], v[98:101]
	v_mfma_f32_16x16x32_bf16 v[90:93], v[174:177], v[206:209], v[90:93]
	v_mfma_f32_16x16x32_bf16 v[82:85], v[182:185], v[206:209], v[82:85]
	v_mfma_f32_16x16x32_bf16 v[74:77], v[174:177], v[214:217], v[74:77]
	v_mfma_f32_16x16x32_bf16 v[66:69], v[182:185], v[214:217], v[66:69]
	s_barrier
	s_add_i32 s98, s75, s23
	s_add_i32 m0, s98, 0xffffff80
	ds_read_b128 v[186:189], v167 offset:49152
	ds_read_b128 v[190:193], v167 offset:50176
	ds_read_b128 v[194:197], v167 offset:51200
	ds_read_b128 v[198:201], v167 offset:52224
	ds_read_b128 v[202:205], v167 offset:53248
	ds_read_b128 v[206:209], v167 offset:54272
	ds_read_b128 v[210:213], v167 offset:55296
	ds_read_b128 v[214:217], v167 offset:56320
	global_load_lds_dwordx4 v132, s[28:29] offset:128
	s_add_i32 m0, s98, 0x1f80
	s_add_i32 s98, s76, s23
	global_load_lds_dwordx4 v136, s[28:29] offset:128
	s_add_u32 s28, s28, 0x40080
	s_addc_u32 s29, s29, 0
	s_mov_b32 m0, s98
	s_nop 0
	global_load_lds_dwordx4 v132, s[28:29]
	s_add_i32 m0, s98, 0x2000
	s_nop 0
	global_load_lds_dwordx4 v136, s[28:29]
	s_add_i32 m0, s62, 0xffffff80
	s_nop 0
	global_load_lds_dwordx4 v130, s[30:31] offset:128
	s_add_i32 m0, s63, 0xffffff80
	s_nop 0
	global_load_lds_dwordx4 v134, s[30:31] offset:128
	s_waitcnt vmcnt(8)
	s_waitcnt lgkmcnt(0)
	s_barrier
	v_mfma_f32_16x16x32_bf16 v[62:65], v[148:151], v[186:189], v[62:65]
	v_mfma_f32_16x16x32_bf16 v[54:57], v[156:159], v[186:189], v[54:57]
	v_mfma_f32_16x16x32_bf16 v[46:49], v[148:151], v[194:197], v[46:49]
	v_mfma_f32_16x16x32_bf16 v[38:41], v[156:159], v[194:197], v[38:41]
	v_mfma_f32_16x16x32_bf16 v[30:33], v[148:151], v[202:205], v[30:33]
	v_mfma_f32_16x16x32_bf16 v[22:25], v[156:159], v[202:205], v[22:25]
	v_mfma_f32_16x16x32_bf16 v[14:17], v[148:151], v[210:213], v[14:17]
	v_mfma_f32_16x16x32_bf16 v[6:9], v[156:159], v[210:213], v[6:9]
	v_mfma_f32_16x16x32_bf16 v[62:65], v[152:155], v[190:193], v[62:65]
	v_mfma_f32_16x16x32_bf16 v[54:57], v[160:163], v[190:193], v[54:57]
	v_mfma_f32_16x16x32_bf16 v[46:49], v[152:155], v[198:201], v[46:49]
	v_mfma_f32_16x16x32_bf16 v[38:41], v[160:163], v[198:201], v[38:41]
	v_mfma_f32_16x16x32_bf16 v[30:33], v[152:155], v[206:209], v[30:33]
	v_mfma_f32_16x16x32_bf16 v[22:25], v[160:163], v[206:209], v[22:25]
	v_mfma_f32_16x16x32_bf16 v[14:17], v[152:155], v[214:217], v[14:17]
	v_mfma_f32_16x16x32_bf16 v[6:9], v[160:163], v[214:217], v[6:9]
	v_mfma_f32_16x16x32_bf16 v[58:61], v[170:173], v[186:189], v[58:61]
	v_mfma_f32_16x16x32_bf16 v[50:53], v[178:181], v[186:189], v[50:53]
	v_mfma_f32_16x16x32_bf16 v[42:45], v[170:173], v[194:197], v[42:45]
	v_mfma_f32_16x16x32_bf16 v[34:37], v[178:181], v[194:197], v[34:37]
	v_mfma_f32_16x16x32_bf16 v[26:29], v[170:173], v[202:205], v[26:29]
	v_mfma_f32_16x16x32_bf16 v[18:21], v[178:181], v[202:205], v[18:21]
	v_mfma_f32_16x16x32_bf16 v[10:13], v[170:173], v[210:213], v[10:13]
	v_mfma_f32_16x16x32_bf16 v[2:5], v[178:181], v[210:213], v[2:5]
	v_mfma_f32_16x16x32_bf16 v[58:61], v[174:177], v[190:193], v[58:61]
	v_mfma_f32_16x16x32_bf16 v[50:53], v[182:185], v[190:193], v[50:53]
	v_mfma_f32_16x16x32_bf16 v[42:45], v[174:177], v[198:201], v[42:45]
	v_mfma_f32_16x16x32_bf16 v[34:37], v[182:185], v[198:201], v[34:37]
	v_mfma_f32_16x16x32_bf16 v[26:29], v[174:177], v[206:209], v[26:29]
	v_mfma_f32_16x16x32_bf16 v[18:21], v[182:185], v[206:209], v[18:21]
	v_mfma_f32_16x16x32_bf16 v[10:13], v[174:177], v[214:217], v[10:13]
	v_mfma_f32_16x16x32_bf16 v[2:5], v[182:185], v[214:217], v[2:5]
	s_barrier
	s_add_i32 s74, s74, 2
	s_add_u32 s58, s58, 0x100
	s_addc_u32 s59, s59, 0
	s_add_u32 s72, s72, 0x100
	s_addc_u32 s73, s73, 0
	s_cmp_gt_u32 s74, 13
	s_cbranch_scc0 .LBB0_1905
	s_and_b64 vcc, exec, s[42:43]
	s_cbranch_vccz .LBB0_1908
	s_barrier
